# attention unit prologue: second K/V tile's loads issued together with the first tile's into free registers (were issued only after the first tile's LDS writes)
# speedup vs baseline: 1.0002x; 1.0002x over previous
; #define LAS __attribute__((address_space(3)))
; __device__ __forceinline__ void attn_unit(LAS unsigned char* lds, const bf16* Qh, const bf16* Kh, const bf16* VTh, const float* nrm, bf16* Y, const float* subln, float lam, int b, int h, int qb) {
;     ...
;     const int tid = tid_, lane = tid & 63, r32 = lane & 31, hi = lane >> 5, wid = __builtin_amdgcn_readfirstlane(tid >> 6);
;     const int wq = wid & 3, comp = wid >> 2;
;     const size_t tokb = (size_t)b * SEQ; const int q0 = qb * 128, qw0 = q0 + wq * 32;
;     const int bh = b * 16 + h;
;     const int qso = OFF_Q + wid * 4096 + lane * 16;
;     { const bf16* qp = Qh + ((size_t)bh * 4096 + qw0 + r32) * 128 + comp * 64 + hi * 8;
; #pragma unroll
;       for (int d0 = 0; d0 < 4; ++d0) *(LAS bf16x8*)(lds + qso + d0 * 1024) = *(const bf16x8*)(qp + d0 * 16); }
;     const char* kgb = (const char*)(Kh + (size_t)bh * 4096 * 128);
;     const char* vgb = (const char*)(VTh + (size_t)bh * 4096 * 128);
;     const unsigned goff = (unsigned)tid * 16u;
;     const int kl0 = OFF_K + (tid >> 4) * KROW + (tid & 15) * 16, vl0 = OFF_V + (tid >> 3) * VROW + (tid & 7) * 16;
;     const int sig = (r32 & ~12) | ((r32 & 4) << 1) | ((r32 & 8) >> 1);
;     const int kfo = OFF_K + sig * KROW + comp * 128 + hi * 16;
;     const int vfo = OFF_V + r32 * VROW + hi * 16;
;     LAS float* wsf = (LAS float*)(lds + OFF_WS) + wid * 64;
;     LAS float* tminb = (LAS float*)(lds + OFF_TMIN);
;     const float slope2 = exp2f(-0.5f * (float)(h + 1)) * LOG2E;
;     const int qpos = qw0 + r32;
;     const int u0 = 2 * qb, u1 = 2 * qb + 1, u2 = (qb == 0) ? 2 : (qb == 31 ? 61 : 2 * qb - 1), u3 = (qb == 0) ? 3 : (qb == 31 ? 60 : 2 * qb + 2);
;     int ktv = (lane == 0) ? u0 : (lane == 1) ? u1 : (lane == 2) ? u2 : u3;
;     const float* nb = nrm + (size_t)b * 64 * 64;
;     const float k2a = nb[lane * 64 + 32 + 2 * h], k2b = nb[lane * 64 + 32 + 2 * h + 1];
;     const float q2a = fmaxf(nb[u0 * 64 + 2 * h], nb[u1 * 64 + 2 * h]), q2b = fmaxf(nb[u0 * 64 + 2 * h + 1], nb[u1 * 64 + 2 * h + 1]);
;     f32x16 o[4];
; #pragma unroll
;     for (int i = 0; i < 4; ++i) o[i] = f32x16{};
;     float mhat = 0.f, lsum = 0.f, tmax = -INFINITY; bool resc = false;
;     v4u pw[4] = {};
;     v4u kreg[2], vreg[2];
;     ...
;     ATT_LOAD(u0); ATT_STORE(0); ATT_LOAD(u1);
.LBB0_911:
	s_or_b64 exec, exec, s[10:11]
	v_mov_b32_e32 v0, s94
	s_waitcnt lgkmcnt(0)
	s_barrier
	ds_read_b32 v0, v0
	s_waitcnt lgkmcnt(0)
	v_cmp_gt_i32_e32 vcc, 0, v0
	v_readfirstlane_b32 s0, v0
	s_cbranch_vccnz .LBB0_921
	s_lshr_b32 s1, s0, 8
	s_and_b32 s3, s0, 0x80
	s_sub_i32 s5, 15, s1
	v_mov_b32_e32 v6, v248
	s_cmp_eq_u32 s3, 0
	s_cselect_b32 s5, s5, s1
	v_readfirstlane_b32 s81, v6
	s_ashr_i32 s1, s81, 6
	s_and_b32 s3, s0, 31
	s_and_b32 s14, s1, 3
	s_bfe_u32 s80, s0, 0x20005
	s_lshl_b32 s0, s3, 7
	s_lshl_b32 s6, s14, 5
	s_or_b32 s18, s6, s0
	s_lshl_b32 s6, s80, 4
	s_add_i32 s6, s6, s5
	s_ashr_i32 s7, s6, 31
	s_lshl_b64 s[10:11], s[6:7], 12
	v_and_b32_e32 v202, 31, v6
	s_or_b32 s10, s10, s18
	s_ashr_i32 s15, s81, 8
	v_or_b32_e32 v0, s10, v202
	v_mov_b32_e32 v1, s11
	v_lshlrev_b64 v[0:1], 8, v[0:1]
	s_lshl_b32 s10, s15, 6
	v_bfe_u32 v201, v6, 5, 1
	v_lshl_add_u64 v[0:1], s[26:27], 0, v[0:1]
	s_ashr_i32 s11, s10, 31
	v_and_b32_e32 v203, 63, v6
	v_lshl_add_u64 v[0:1], s[10:11], 1, v[0:1]
	v_lshlrev_b32_e32 v180, 4, v201
	v_mov_b32_e32 v181, v177
	v_lshl_add_u64 v[4:5], v[0:1], 0, v[180:181]
	v_lshl_add_u32 v0, v203, 4, 0
	s_lshl_b32 s12, s1, 12
	v_add_u32_e32 v0, 0x1ac80, v0
	v_add_u32_e32 v210, s12, v0
	global_load_dwordx4 v[128:131], v[4:5], off
	global_load_dwordx4 v[132:135], v[4:5], off offset:32
	global_load_dwordx4 v[136:139], v[4:5], off offset:64
	global_load_dwordx4 v[140:143], v[4:5], off offset:96
	s_lshl_b64 s[12:13], s[6:7], 20
	s_movk_i32 s6, 0x110
	s_add_u32 s68, s38, s12
	s_addc_u32 s69, s39, s13
	s_lshl_b32 s64, s15, 7
	v_lshlrev_b32_e32 v176, 6, v203
	v_lshlrev_b32_e32 v216, 4, v6
	v_lshl_add_u32 v8, s3, 15, v216
	v_add_u32_e32 v12, 0x2000, v8
	v_and_b32_e32 v32, 0xf0, v216
	v_and_b32_e32 v34, 0x70, v216
	v_lshlrev_b32_e32 v209, 3, v201
	v_or_b32_e32 v212, s18, v202
	v_lshrrev_b32_e32 v0, 4, v6
	v_mul_lo_u32 v30, v0, s6
	v_lshrrev_b32_e32 v0, 3, v6
	v_lshlrev_b32_e32 v1, 1, v6
	v_lshrrev_b32_e32 v2, 1, v6
	v_mul_lo_u32 v31, v0, s83
	v_and_b32_e32 v0, 19, v6
	v_and_b32_e32 v1, 8, v1
	v_and_b32_e32 v2, 4, v2
	s_add_i32 s6, s5, 1
	v_or3_b32 v2, v0, v1, v2
	v_cvt_f32_i32_e32 v0, s6
	s_mov_b32 s6, 0xc2fc0000
	v_mul_u32_u24_e32 v33, 0x110, v2
	v_add3_u32 v16, 0, v30, v32
	v_mul_f32_e32 v1, -0.5, v0
	v_cmp_gt_f32_e32 vcc, s6, v1
	s_and_b64 s[6:7], vcc, exec
	s_cselect_b32 s6, 0xffffffc0, 0
	v_cndmask_b32_e32 v1, 0, v249, vcc
	v_fmac_f32_e32 v1, -0.5, v0
	v_exp_f32_e32 v0, v1
	v_cmp_eq_u32_e32 vcc, 1, v203
	v_ldexp_f32 v0, v0, s6
	s_lshl_b32 s6, s3, 1
	s_or_b32 s24, s6, 1
	s_add_i32 s7, s6, -1
	s_add_i32 s10, s6, 2
	s_cmp_lg_u32 s3, 31
	s_cselect_b32 s10, s10, 60
	s_cmp_eq_u32 s3, 0
	s_cselect_b32 s33, 2, s7
	s_cselect_b32 s25, 3, s10
	v_mul_f32_e32 v208, 0x3fb8aa3b, v0
	v_cmp_eq_u32_e64 s[10:11], 2, v203
	v_mov_b32_e32 v0, s25
	v_mov_b32_e32 v1, s33
	s_lshl_b32 s7, s80, 14
	v_cndmask_b32_e64 v0, v0, v1, s[10:11]
	s_add_u32 s10, s35, s7
	s_addc_u32 s11, s92, 0
	s_lshl_b32 s16, s5, 1
	s_add_i32 s66, s16, s0
	s_ashr_i32 s67, s66, 31
	s_ashr_i32 s17, s16, 31
	s_lshl_b64 s[66:67], s[66:67], 2
	s_add_u32 s66, s10, s66
	v_mov_b32_e32 v1, s24
	s_addc_u32 s67, s11, s67
	s_lshl_b32 s7, s24, 6
	v_cndmask_b32_e32 v3, v0, v1, vcc
	v_lshl_add_u64 v[0:1], s[16:17], 0, v[176:177]
	s_add_i32 s16, s7, s16
	s_ashr_i32 s17, s16, 31
	s_lshl_b64 s[16:17], s[16:17], 2
	v_lshl_add_u64 v[0:1], v[0:1], 2, s[10:11]
	s_add_u32 s10, s10, s16
	s_addc_u32 s11, s11, s17
	s_add_u32 s70, s42, s12
	global_load_dwordx2 v[24:25], v[0:1], off offset:128
	global_load_dwordx2 v[26:27], v177, s[66:67]
	s_addc_u32 s71, s43, s13
	v_cmp_eq_u32_e64 s[12:13], 0, v203
	v_mov_b32_e32 v0, s6
	global_load_dwordx2 v[28:29], v177, s[10:11]
	v_cndmask_b32_e64 v213, v3, v0, s[12:13]
	global_load_dwordx4 v[0:3], v8, s[70:71]
	global_load_dwordx4 v[4:7], v12, s[70:71]
	s_nop 0
	global_load_dwordx4 v[8:11], v8, s[68:69]
	s_nop 0
	global_load_dwordx4 v[12:15], v12, s[68:69]
	v_lshl_add_u32 v160, s24, 14, v216
	v_add_u32_e32 v161, 0x2000, v160
	global_load_dwordx4 v[144:147], v160, s[70:71]
	global_load_dwordx4 v[148:151], v161, s[70:71]
	global_load_dwordx4 v[152:155], v160, s[68:69]
	global_load_dwordx4 v[156:159], v161, s[68:69]
	v_readlane_b32 s3, v213, 2
	s_add_i32 s7, s64, 0
	v_add3_u32 v217, s7, v33, v180
	s_waitcnt vmcnt(11)
	ds_write_b128 v210, v[128:131]
	ds_write_b128 v210, v[132:135] offset:1024
	ds_write_b128 v210, v[136:139] offset:2048
	ds_write_b128 v210, v[140:143] offset:3072
	s_waitcnt vmcnt(7)
	ds_write_b128 v16, v[0:3]
	s_waitcnt vmcnt(6)
	ds_write_b128 v16, v[4:7] offset:8704
	v_add3_u32 v0, 0, v31, v34
	s_waitcnt vmcnt(5)
	ds_write_b128 v0, v[8:11] offset:52224
	s_waitcnt vmcnt(4)
	ds_write_b128 v0, v[12:15] offset:61440
	v_add_u32_e32 v17, 0xcc00, v0
	s_waitcnt lgkmcnt(0)
	s_barrier
	s_waitcnt vmcnt(3)
	ds_write_b128 v16, v[144:147] offset:17408
	s_waitcnt vmcnt(2)
	ds_write_b128 v16, v[148:151] offset:26112
	s_waitcnt vmcnt(1)
	ds_write_b128 v17, v[152:155] offset:18432
	s_waitcnt vmcnt(0)
	ds_write_b128 v17, v[156:159] offset:27648
	v_lshl_add_u32 v0, s3, 14, v216
	v_add_u32_e32 v1, 0x2000, v0
	global_load_dwordx4 v[128:131], v0, s[70:71]
	global_load_dwordx4 v[132:135], v1, s[70:71]
	global_load_dwordx4 v[136:139], v0, s[68:69]
	global_load_dwordx4 v[140:143], v1, s[68:69]
	v_readlane_b32 s3, v213, 0
	s_lshl_b32 s3, s3, 6
	s_or_b32 s7, s3, 63
	v_or_b32_e32 v0, s3, v209
	v_sub_u32_e32 v16, v212, v0
	ds_read_b128 v[12:15], v210
	ds_read_b128 v[8:11], v210 offset:1024
	ds_read_b128 v[4:7], v210 offset:2048
	ds_read_b128 v[0:3], v210 offset:3072
	s_cmp_lt_i32 s7, s18
	v_cvt_f32_i32_e32 v35, v16
	ds_read_b128 v[20:23], v217
	ds_read_b128 v[16:19], v217 offset:8704
	s_cselect_b64 s[10:11], -1, 0
	s_or_b32 s7, s18, 31
	s_cmp_gt_i32 s3, s7
	s_cselect_b64 s[16:17], -1, 0
	s_or_b64 s[66:67], s[10:11], s[16:17]
	s_mov_b64 s[16:17], -1
	s_andn2_b64 vcc, exec, s[66:67]
	s_cbranch_vccz .LBB0_914
	v_add_f32_e32 v36, v35, v179
	v_xor_b32_e32 v39, 0x80000000, v208
	v_add_f32_e32 v37, v36, v179
	v_fma_f32 v72, |v36|, v39, v184
	v_add_f32_e32 v40, v35, v185
	v_add_f32_e32 v36, v36, v185
	v_fma_f32 v64, |v35|, v39, v184
	s_mov_b64 s[16:17], 0
	v_add_f32_e32 v38, v37, v179
	v_fma_f32 v80, |v37|, v39, v184
	v_add_f32_e32 v37, v37, v185
	v_fma_f32 v65, |v40|, v39, v184
	v_fma_f32 v73, |v36|, v39, v184
	v_add_f32_e32 v40, v40, v185
	v_fma_f32 v88, |v38|, v39, v184
	v_add_f32_e32 v38, v38, v185
	v_fma_f32 v81, |v37|, v39, v184
	v_add_f32_e32 v36, v36, v185
	v_add_f32_e32 v37, v37, v185
	v_fma_f32 v66, |v40|, v39, v184
	v_add_f32_e32 v40, v40, v185
	v_fma_f32 v89, |v38|, v39, v184
	v_add_f32_e32 v38, v38, v185
	v_fma_f32 v74, |v36|, v39, v184
	v_fma_f32 v82, |v37|, v39, v184
	v_add_f32_e32 v36, v36, v185
	v_add_f32_e32 v37, v37, v185
	v_fma_f32 v67, |v40|, v39, v184
	v_fma_f32 v90, |v38|, v39, v184
	v_add_f32_e32 v38, v38, v185
	v_add_f32_e32 v40, v40, v185
	v_fma_f32 v75, |v36|, v39, v184
	v_fma_f32 v83, |v37|, v39, v184
	v_add_f32_e32 v36, v36, v185
	v_add_f32_e32 v37, v37, v185
	v_fma_f32 v91, |v38|, v39, v184
	v_add_f32_e32 v38, v38, v185
	v_fma_f32 v68, |v40|, v39, v184
	v_add_f32_e32 v40, v40, v185
	v_fma_f32 v76, |v36|, v39, v184
	v_fma_f32 v84, |v37|, v39, v184
	v_add_f32_e32 v36, v36, v185
	v_fma_f32 v92, |v38|, v39, v184
	v_add_f32_e32 v37, v37, v185
	v_add_f32_e32 v38, v38, v185
	v_fma_f32 v69, |v40|, v39, v184
	v_add_f32_e32 v40, v40, v185
	v_fma_f32 v77, |v36|, v39, v184
	v_add_f32_e32 v36, v36, v185
	v_fma_f32 v85, |v37|, v39, v184
	v_fma_f32 v93, |v38|, v39, v184
	v_add_f32_e32 v37, v37, v185
	v_add_f32_e32 v38, v38, v185
	v_fma_f32 v70, |v40|, v39, v184
	v_fma_f32 v78, |v36|, v39, v184
	v_add_f32_e32 v40, v40, v185
	v_add_f32_e32 v36, v36, v185
	v_fma_f32 v86, |v37|, v39, v184
	v_fma_f32 v94, |v38|, v39, v184
	v_add_f32_e32 v37, v37, v185
	v_add_f32_e32 v38, v38, v185
	v_fma_f32 v71, |v40|, v39, v184
	v_fma_f32 v79, |v36|, v39, v184
	v_fma_f32 v87, |v37|, v39, v184
	v_fma_f32 v95, |v38|, v39, v184
